# previous + retention state update: LDS fragment reads issued ahead of their MFMAs (counted lgkmcnt)
# speedup vs baseline: 1.0925x; 1.0004x over previous
; DI float bf2f(u16 v) { return __uint_as_float(((unsigned)v) << 16); }
; DI int ltid() { int t = __builtin_amdgcn_workitem_id_x(); asm volatile("" : "+v"(t)); return t; }
; DI void build_kt(char* kt, const u16* __restrict__ QK, int row0, int h, float lg2, bool fwd) {
;   const int tid = ltid();
; #pragma unroll
;   for (int j = 0; j < 4; ++j) {
;     const int idx = tid + 256 * j;
;     const int m = idx >> 3, dc = idx & 7;
;     const u32x4 raw = *(const u32x4*)(QK + (size_t)(row0 + m) * 1024 + 512 + h * 64 + dc * 8);
;     const float dec = exp2f(lg2 * (float)(fwd ? (127 - m) : m));
; #pragma unroll
;     for (int i = 0; i < 8; ++i) {
;       const u16 e = (u16)((i & 1) ? (raw[i >> 1] >> 16) : (raw[i >> 1] & 0xffffu));
;       const int d = dc * 8 + i;
;       *(u16*)(kt + d * 256 + ((((m >> 3) ^ (d & 15)) << 4) | ((m & 7) << 1))) = f2bf(bf2f(e) * dec);
;     }
;   }
; }
; DI void state_update(f32x16 (&S)[2], const char* kt, const u16* __restrict__ vt_rows  ,
;                      float cd, int lane) {
;   const int r = lane & 31, h5 = lane >> 5;
; #pragma unroll
;   for (int i = 0; i < 16; ++i) { S[0][i] *= cd; S[1][i] *= cd; }
.LBB0_473:
	s_and_b64 s[4:5], s[46:47], exec
	s_cselect_b32 s4, s34, s6
	v_mov_b32_e32 v34, v196
	s_barrier
	s_add_i32 s4, s88, s4
	v_ashrrev_i32_e32 v42, 3, v34
	v_add_u32_e32 v36, s4, v42
	v_lshlrev_b32_e32 v41, 3, v34
	v_ashrrev_i32_e32 v37, 31, v36
	v_and_b32_e32 v35, 56, v41
	v_lshlrev_b64 v[36:37], 11, v[36:37]
	v_lshl_add_u64 v[36:37], s[42:43], 0, v[36:37]
	v_lshlrev_b32_e32 v0, 1, v35
	v_lshl_add_u64 v[36:37], v[36:37], 0, v[0:1]
	v_add_co_u32_e32 v110, vcc, 0x10000, v36
	s_nop 1
	v_addc_co_u32_e32 v111, vcc, 0, v37, vcc
	global_load_dwordx4 v[52:55], v[36:37], off offset:1024
	global_load_dwordx4 v[76:79], v[110:111], off offset:1024
	v_add_co_u32_e32 v110, vcc, 0x10000, v110
	s_nop 1
	v_addc_co_u32_e32 v111, vcc, 0, v111, vcc
	global_load_dwordx4 v[80:83], v[110:111], off offset:1024
	v_add_co_u32_e32 v110, vcc, 0x10000, v110
	s_nop 1
	v_addc_co_u32_e32 v111, vcc, 0, v111, vcc
	global_load_dwordx4 v[84:87], v[110:111], off offset:1024
	v_cvt_f32_i32_e32 v36, v42
	v_lshlrev_b32_e32 v42, 1, v42
	v_and_b32_e32 v57, 14, v42
	v_pk_mul_f32 v[2:3], v[38:39], v[2:3]
	v_mul_f32_e32 v37, v170, v36
	v_cmp_gt_f32_e32 vcc, s13, v37
	v_pk_mul_f32 v[18:19], v[38:39], v[18:19]
	v_pk_mul_f32 v[4:5], v[38:39], v[4:5]
	v_cndmask_b32_e32 v37, 0, v203, vcc
	v_fmac_f32_e32 v37, v170, v36
	v_exp_f32_e32 v36, v37
	v_cndmask_b32_e32 v37, 0, v204, vcc
	v_pk_mul_f32 v[20:21], v[38:39], v[20:21]
	v_pk_mul_f32 v[6:7], v[38:39], v[6:7]
	v_ldexp_f32 v36, v36, v37
	v_ashrrev_i32_e32 v37, 6, v34
	v_bitop3_b32 v44, v41, v37, 8 bitop3:0x6c
	v_pk_mul_f32 v[22:23], v[38:39], v[22:23]
	v_pk_mul_f32 v[8:9], v[38:39], v[8:9]
	v_pk_mul_f32 v[24:25], v[38:39], v[24:25]
	v_pk_mul_f32 v[10:11], v[38:39], v[10:11]
	v_pk_mul_f32 v[26:27], v[38:39], v[26:27]
	v_pk_mul_f32 v[12:13], v[38:39], v[12:13]
	v_pk_mul_f32 v[28:29], v[38:39], v[28:29]
	v_pk_mul_f32 v[14:15], v[38:39], v[14:15]
	v_pk_mul_f32 v[30:31], v[38:39], v[30:31]
	v_pk_mul_f32 v[16:17], v[38:39], v[16:17]
	v_pk_mul_f32 v[32:33], v[38:39], v[32:33]
	s_waitcnt vmcnt(3)
	v_lshlrev_b32_e32 v42, 16, v52
	v_mul_f32_e32 v42, v36, v42
	v_cvt_pk_bf16_f32 v43, v42, s0
	v_lshlrev_b32_e32 v42, 8, v35
	v_lshl_add_u32 v44, v44, 4, v42
	v_or_b32_e32 v44, v44, v57
	ds_write_b16 v44, v43 offset:32768
	v_or_b32_e32 v43, 1, v35
	v_and_b32_e32 v44, 0xffff0000, v52
	v_lshlrev_b32_e32 v45, 8, v43
	v_bitop3_b32 v46, v43, v37, 9 bitop3:0x6c
	v_mul_f32_e32 v44, v36, v44
	v_lshl_add_u32 v46, v46, 4, v45
	v_cvt_pk_bf16_f32 v44, v44, s0
	v_or_b32_e32 v46, v46, v57
	ds_write_b16 v46, v44 offset:32768
	v_lshlrev_b32_e32 v46, 16, v53
	v_or_b32_e32 v44, 2, v35
	v_mul_f32_e32 v46, v36, v46
	v_cvt_pk_bf16_f32 v47, v46, s0
	v_lshlrev_b32_e32 v46, 8, v44
	v_bitop3_b32 v48, v44, v37, 10 bitop3:0x6c
	v_lshl_add_u32 v48, v48, 4, v46
	v_or_b32_e32 v48, v48, v57
	ds_write_b16 v48, v47 offset:32768
	v_or_b32_e32 v47, 3, v35
	v_and_b32_e32 v48, 0xffff0000, v53
	v_lshlrev_b32_e32 v49, 8, v47
	v_bitop3_b32 v50, v47, v37, 11 bitop3:0x6c
	v_mul_f32_e32 v48, v36, v48
	v_lshl_add_u32 v50, v50, 4, v49
	v_cvt_pk_bf16_f32 v48, v48, s0
	v_or_b32_e32 v50, v50, v57
	ds_write_b16 v50, v48 offset:32768
	v_lshlrev_b32_e32 v50, 16, v54
	v_or_b32_e32 v48, 4, v35
	v_mul_f32_e32 v50, v36, v50
	v_cvt_pk_bf16_f32 v51, v50, s0
	v_lshlrev_b32_e32 v50, 8, v48
	v_bitop3_b32 v52, v48, v37, 12 bitop3:0x6c
	v_lshl_add_u32 v52, v52, 4, v50
	v_or_b32_e32 v52, v52, v57
	ds_write_b16 v52, v51 offset:32768
	v_or_b32_e32 v51, 5, v35
	v_and_b32_e32 v52, 0xffff0000, v54
	v_lshlrev_b32_e32 v53, 8, v51
	v_bitop3_b32 v54, v51, v37, 13 bitop3:0x6c
	v_mul_f32_e32 v52, v36, v52
	v_lshl_add_u32 v54, v54, 4, v53
	v_cvt_pk_bf16_f32 v52, v52, s0
	v_or_b32_e32 v54, v54, v57
	ds_write_b16 v54, v52 offset:32768
	v_lshlrev_b32_e32 v54, 16, v55
	v_or_b32_e32 v52, 6, v35
	v_mul_f32_e32 v54, v36, v54
	v_cvt_pk_bf16_f32 v56, v54, s0
	v_lshlrev_b32_e32 v54, 8, v52
	v_bitop3_b32 v58, v52, v37, 14 bitop3:0x6c
	v_lshl_add_u32 v58, v58, 4, v54
	v_or_b32_e32 v58, v58, v57
	ds_write_b16 v58, v56 offset:32768
	v_and_b32_e32 v56, 0xffff0000, v55
	v_or_b32_e32 v55, 7, v35
	v_mul_f32_e32 v35, v36, v56
	v_lshlrev_b32_e32 v56, 8, v55
	v_bitop3_b32 v36, v55, v37, 15 bitop3:0x6c
	v_lshl_add_u32 v36, v36, 4, v56
	v_cvt_pk_bf16_f32 v35, v35, s0
	v_or_b32_e32 v36, v36, v57
	ds_write_b16 v36, v35 offset:32768
	v_add_u32_e32 v35, 0x100, v34
	v_ashrrev_i32_e32 v57, 3, v35
	v_add_u32_e32 v36, s4, v57
	v_ashrrev_i32_e32 v37, 31, v36
	v_lshlrev_b64 v[36:37], 11, v[36:37]
	v_lshl_add_u64 v[36:37], s[42:43], 0, v[36:37]
	v_lshl_add_u64 v[36:37], v[36:37], 0, v[0:1]
	v_cvt_f32_i32_e32 v36, v57
	v_ashrrev_i32_e32 v35, 6, v35
	v_bitop3_b32 v62, v41, v35, 8 bitop3:0x6c
	v_lshl_add_u32 v62, v62, 4, v42
	v_mul_f32_e32 v37, v170, v36
	v_cmp_gt_f32_e32 vcc, s13, v37
	s_nop 1
	v_cndmask_b32_e32 v37, 0, v203, vcc
	v_fmac_f32_e32 v37, v170, v36
	v_exp_f32_e32 v36, v37
	v_cndmask_b32_e32 v37, 0, v204, vcc
	v_ldexp_f32 v36, v36, v37
	v_lshlrev_b32_e32 v37, 1, v57
	v_and_b32_e32 v37, 14, v37
	v_or_b32_e32 v62, v62, v37
	s_waitcnt vmcnt(2)
; DI float bf2f(u16 v) { return __uint_as_float(((unsigned)v) << 16); }
; DI void build_kt(char* kt, const u16* __restrict__ QK, int row0, int h, float lg2, bool fwd) {
;     ...
;   for (int j = 0; j < 4; ++j) {
;     const int idx = tid + 256 * j;
;     const int m = idx >> 3, dc = idx & 7;
;     const u32x4 raw = *(const u32x4*)(QK + (size_t)(row0 + m) * 1024 + 512 + h * 64 + dc * 8);
;     const float dec = exp2f(lg2 * (float)(fwd ? (127 - m) : m));
; #pragma unroll
;     for (int i = 0; i < 8; ++i) {
;       const u16 e = (u16)((i & 1) ? (raw[i >> 1] >> 16) : (raw[i >> 1] & 0xffffu));
;       const int d = dc * 8 + i;
;       *(u16*)(kt + d * 256 + ((((m >> 3) ^ (d & 15)) << 4) | ((m & 7) << 1))) = f2bf(bf2f(e) * dec);
;     }
	v_lshlrev_b32_e32 v57, 16, v76
	v_mul_f32_e32 v57, v36, v57
	v_cvt_pk_bf16_f32 v57, v57, s0
	ds_write_b16 v62, v57 offset:32768
	v_and_b32_e32 v57, 0xffff0000, v76
	v_bitop3_b32 v58, v43, v35, 9 bitop3:0x6c
	v_mul_f32_e32 v57, v36, v57
	v_lshl_add_u32 v58, v58, 4, v45
	v_cvt_pk_bf16_f32 v57, v57, s0
	v_or_b32_e32 v58, v58, v37
	ds_write_b16 v58, v57 offset:32768
	v_lshlrev_b32_e32 v57, 16, v77
	v_bitop3_b32 v58, v44, v35, 10 bitop3:0x6c
	v_mul_f32_e32 v57, v36, v57
	v_lshl_add_u32 v58, v58, 4, v46
	v_cvt_pk_bf16_f32 v57, v57, s0
	v_or_b32_e32 v58, v58, v37
	ds_write_b16 v58, v57 offset:32768
	v_and_b32_e32 v57, 0xffff0000, v77
	v_bitop3_b32 v58, v47, v35, 11 bitop3:0x6c
	v_mul_f32_e32 v57, v36, v57
	v_lshl_add_u32 v58, v58, 4, v49
	v_cvt_pk_bf16_f32 v57, v57, s0
	v_or_b32_e32 v58, v58, v37
	ds_write_b16 v58, v57 offset:32768
	v_lshlrev_b32_e32 v57, 16, v78
	v_bitop3_b32 v58, v48, v35, 12 bitop3:0x6c
	v_mul_f32_e32 v57, v36, v57
	v_lshl_add_u32 v58, v58, 4, v50
	v_cvt_pk_bf16_f32 v57, v57, s0
	v_or_b32_e32 v58, v58, v37
	ds_write_b16 v58, v57 offset:32768
	v_and_b32_e32 v57, 0xffff0000, v78
	v_bitop3_b32 v58, v51, v35, 13 bitop3:0x6c
	v_mul_f32_e32 v57, v36, v57
	v_lshl_add_u32 v58, v58, 4, v53
	v_cvt_pk_bf16_f32 v57, v57, s0
	v_or_b32_e32 v58, v58, v37
	ds_write_b16 v58, v57 offset:32768
	v_lshlrev_b32_e32 v57, 16, v79
	v_bitop3_b32 v58, v52, v35, 14 bitop3:0x6c
	v_mul_f32_e32 v57, v36, v57
	v_lshl_add_u32 v58, v58, 4, v54
	v_cvt_pk_bf16_f32 v57, v57, s0
	v_or_b32_e32 v58, v58, v37
	ds_write_b16 v58, v57 offset:32768
	v_and_b32_e32 v57, 0xffff0000, v79
	v_bitop3_b32 v35, v55, v35, 15 bitop3:0x6c
	v_mul_f32_e32 v36, v36, v57
	v_lshl_add_u32 v35, v35, 4, v56
	v_cvt_pk_bf16_f32 v36, v36, s0
	v_or_b32_e32 v35, v35, v37
	ds_write_b16 v35, v36 offset:32768
	v_add_u32_e32 v35, 0x200, v34
	v_ashrrev_i32_e32 v57, 3, v35
	v_add_u32_e32 v36, s4, v57
	v_ashrrev_i32_e32 v37, 31, v36
	v_lshlrev_b64 v[36:37], 11, v[36:37]
	v_lshl_add_u64 v[36:37], s[42:43], 0, v[36:37]
	v_lshl_add_u64 v[36:37], v[36:37], 0, v[0:1]
	v_cvt_f32_i32_e32 v36, v57
	v_ashrrev_i32_e32 v35, 6, v35
	v_bitop3_b32 v62, v41, v35, 8 bitop3:0x6c
	v_lshl_add_u32 v62, v62, 4, v42
	v_mul_f32_e32 v37, v170, v36
	v_cmp_gt_f32_e32 vcc, s13, v37
	s_nop 1
	v_cndmask_b32_e32 v37, 0, v203, vcc
	v_fmac_f32_e32 v37, v170, v36
	v_exp_f32_e32 v36, v37
	v_cndmask_b32_e32 v37, 0, v204, vcc
	v_ldexp_f32 v36, v36, v37
	v_lshlrev_b32_e32 v37, 1, v57
	v_and_b32_e32 v37, 14, v37
	v_or_b32_e32 v62, v62, v37
	s_waitcnt vmcnt(1)
	v_lshlrev_b32_e32 v57, 16, v80
	v_mul_f32_e32 v57, v36, v57
	v_cvt_pk_bf16_f32 v57, v57, s0
	ds_write_b16 v62, v57 offset:32768
	v_and_b32_e32 v57, 0xffff0000, v80
	v_bitop3_b32 v58, v43, v35, 9 bitop3:0x6c
	v_mul_f32_e32 v57, v36, v57
	v_lshl_add_u32 v58, v58, 4, v45
	v_cvt_pk_bf16_f32 v57, v57, s0
	v_or_b32_e32 v58, v58, v37
	ds_write_b16 v58, v57 offset:32768
	v_lshlrev_b32_e32 v57, 16, v81
	v_bitop3_b32 v58, v44, v35, 10 bitop3:0x6c
	v_mul_f32_e32 v57, v36, v57
	v_lshl_add_u32 v58, v58, 4, v46
	v_cvt_pk_bf16_f32 v57, v57, s0
	v_or_b32_e32 v58, v58, v37
	ds_write_b16 v58, v57 offset:32768
	v_and_b32_e32 v57, 0xffff0000, v81
	v_bitop3_b32 v58, v47, v35, 11 bitop3:0x6c
	v_mul_f32_e32 v57, v36, v57
	v_lshl_add_u32 v58, v58, 4, v49
	v_cvt_pk_bf16_f32 v57, v57, s0
	v_or_b32_e32 v58, v58, v37
	ds_write_b16 v58, v57 offset:32768
	v_lshlrev_b32_e32 v57, 16, v82
	v_bitop3_b32 v58, v48, v35, 12 bitop3:0x6c
	v_mul_f32_e32 v57, v36, v57
	v_lshl_add_u32 v58, v58, 4, v50
	v_cvt_pk_bf16_f32 v57, v57, s0
	v_or_b32_e32 v58, v58, v37
	ds_write_b16 v58, v57 offset:32768
	v_and_b32_e32 v57, 0xffff0000, v82
	v_bitop3_b32 v58, v51, v35, 13 bitop3:0x6c
	v_mul_f32_e32 v57, v36, v57
	v_lshl_add_u32 v58, v58, 4, v53
	v_cvt_pk_bf16_f32 v57, v57, s0
	v_or_b32_e32 v58, v58, v37
	ds_write_b16 v58, v57 offset:32768
	v_lshlrev_b32_e32 v57, 16, v83
	v_bitop3_b32 v58, v52, v35, 14 bitop3:0x6c
	v_mul_f32_e32 v57, v36, v57
	v_lshl_add_u32 v58, v58, 4, v54
	v_cvt_pk_bf16_f32 v57, v57, s0
	v_or_b32_e32 v58, v58, v37
	ds_write_b16 v58, v57 offset:32768
	v_and_b32_e32 v57, 0xffff0000, v83
	v_mul_f32_e32 v36, v36, v57
	v_bitop3_b32 v35, v55, v35, 15 bitop3:0x6c
	v_add_u32_e32 v57, 0x300, v34
	v_lshl_add_u32 v35, v35, 4, v56
	v_ashrrev_i32_e32 v58, 3, v57
	v_cvt_pk_bf16_f32 v36, v36, s0
	v_or_b32_e32 v35, v35, v37
	v_add_u32_e32 v34, s4, v58
	ds_write_b16 v35, v36 offset:32768
	v_ashrrev_i32_e32 v35, 31, v34
	v_lshlrev_b64 v[34:35], 11, v[34:35]
	v_lshl_add_u64 v[34:35], s[42:43], 0, v[34:35]
	v_lshl_add_u64 v[34:35], v[34:35], 0, v[0:1]
	v_cvt_f32_i32_e32 v0, v58
	v_ashrrev_i32_e32 v57, 6, v57
	v_lshlrev_b32_e32 v58, 1, v58
	v_bitop3_b32 v41, v41, v57, 8 bitop3:0x6c
	v_mul_f32_e32 v59, v170, v0
	v_cmp_gt_f32_e32 vcc, s13, v59
	v_and_b32_e32 v58, 14, v58
	v_lshl_add_u32 v41, v41, 4, v42
	v_cndmask_b32_e32 v59, 0, v203, vcc
	v_fmac_f32_e32 v59, v170, v0
	v_exp_f32_e32 v0, v59
	v_cndmask_b32_e32 v59, 0, v204, vcc
	v_or_b32_e32 v41, v41, v58
	v_ldexp_f32 v0, v0, v59
	s_waitcnt vmcnt(0)
; DI float bf2f(u16 v) { return __uint_as_float(((unsigned)v) << 16); }
; #define MFMA32(a, b, c) __builtin_amdgcn_mfma_f32_32x32x16_bf16((a), (b), (c), 0, 0, 0)
; DI void build_kt(char* kt, const u16* __restrict__ QK, int row0, int h, float lg2, bool fwd) {
;     ...
;     for (int i = 0; i < 8; ++i) {
;       const u16 e = (u16)((i & 1) ? (raw[i >> 1] >> 16) : (raw[i >> 1] & 0xffffu));
;       const int d = dc * 8 + i;
;       *(u16*)(kt + d * 256 + ((((m >> 3) ^ (d & 15)) << 4) | ((m & 7) << 1))) = f2bf(bf2f(e) * dec);
;     }
;   }
; }
; DI void state_update(f32x16 (&S)[2], const char* kt, const u16* __restrict__ vt_rows  ,
;                      float cd, int lane) {
;   const int r = lane & 31, h5 = lane >> 5;
; #pragma unroll
;   for (int i = 0; i < 16; ++i) { S[0][i] *= cd; S[1][i] *= cd; }
; #pragma unroll
;   for (int s = 0; s < 8; ++s) {
;     const bf16x8 bv = *(const bf16x8*)(vt_rows + (size_t)r * VT_LD + s * 16 + h5 * 8);
;     const int ch = 2 * s + h5;
;     const bf16x8 a0 = *(const bf16x8*)(kt + r * 256 + ((ch ^ (r & 15)) << 4));
;     const bf16x8 a1 = *(const bf16x8*)(kt + (32 + r) * 256 + ((ch ^ (r & 15)) << 4));
;     S[0] = MFMA32(a0, bv, S[0]);
;     S[1] = MFMA32(a1, bv, S[1]);
;   }
; }
	v_lshlrev_b32_e32 v59, 16, v84
	v_mul_f32_e32 v59, v0, v59
	v_cvt_pk_bf16_f32 v59, v59, s0
	ds_write_b16 v41, v59 offset:32768
	v_and_b32_e32 v34, 0xffff0000, v84
	v_bitop3_b32 v41, v43, v57, 9 bitop3:0x6c
	v_mul_f32_e32 v34, v0, v34
	v_lshl_add_u32 v41, v41, 4, v45
	v_cvt_pk_bf16_f32 v34, v34, s0
	v_or_b32_e32 v41, v41, v58
	ds_write_b16 v41, v34 offset:32768
	v_lshlrev_b32_e32 v34, 16, v85
	v_bitop3_b32 v41, v44, v57, 10 bitop3:0x6c
	v_mul_f32_e32 v34, v0, v34
	v_lshl_add_u32 v41, v41, 4, v46
	v_cvt_pk_bf16_f32 v34, v34, s0
	v_or_b32_e32 v41, v41, v58
	ds_write_b16 v41, v34 offset:32768
	v_and_b32_e32 v34, 0xffff0000, v85
	v_bitop3_b32 v35, v47, v57, 11 bitop3:0x6c
	v_mul_f32_e32 v34, v0, v34
	v_lshl_add_u32 v35, v35, 4, v49
	v_cvt_pk_bf16_f32 v34, v34, s0
	v_or_b32_e32 v35, v35, v58
	ds_write_b16 v35, v34 offset:32768
	v_lshlrev_b32_e32 v34, 16, v86
	v_bitop3_b32 v35, v48, v57, 12 bitop3:0x6c
	v_mul_f32_e32 v34, v0, v34
	v_lshl_add_u32 v35, v35, 4, v50
	v_cvt_pk_bf16_f32 v34, v34, s0
	v_or_b32_e32 v35, v35, v58
	ds_write_b16 v35, v34 offset:32768
	v_and_b32_e32 v34, 0xffff0000, v86
	v_bitop3_b32 v35, v51, v57, 13 bitop3:0x6c
	v_mul_f32_e32 v34, v0, v34
	v_lshl_add_u32 v35, v35, 4, v53
	v_cvt_pk_bf16_f32 v34, v34, s0
	v_or_b32_e32 v35, v35, v58
	ds_write_b16 v35, v34 offset:32768
	v_lshlrev_b32_e32 v34, 16, v87
	v_bitop3_b32 v35, v52, v57, 14 bitop3:0x6c
	v_mul_f32_e32 v34, v0, v34
	v_lshl_add_u32 v35, v35, 4, v54
	v_cvt_pk_bf16_f32 v34, v34, s0
	v_or_b32_e32 v35, v35, v58
	ds_write_b16 v35, v34 offset:32768
	v_and_b32_e32 v34, 0xffff0000, v87
	v_mul_f32_e32 v0, v0, v34
	v_bitop3_b32 v34, v55, v57, 15 bitop3:0x6c
	v_lshl_add_u32 v34, v34, 4, v56
	v_cvt_pk_bf16_f32 v0, v0, s0
	v_or_b32_e32 v34, v34, v58
	v_ashrrev_i32_e32 v41, 5, v168
	ds_write_b16 v34, v0 offset:32768
	v_lshlrev_b32_e32 v34, 3, v41
	v_ashrrev_i32_e32 v35, 31, v34
	v_lshlrev_b32_e32 v0, 5, v169
	v_and_b32_e32 v36, 31, v168
	v_lshlrev_b64 v[34:35], 1, v[34:35]
	v_mul_u32_u24_e32 v37, 0x900, v36
	v_mad_i64_i32 v[34:35], s[4:5], v0, s12, v[34:35]
	v_lshlrev_b32_e32 v0, 1, v37
	s_add_u32 s4, s44, s0
	v_lshl_add_u64 v[34:35], v[34:35], 0, v[0:1]
	s_addc_u32 s5, s45, s1
	v_lshl_add_u64 v[34:35], s[4:5], 0, v[34:35]
	s_mov_b32 s4, 0xb361000
	v_add_co_u32_e32 v34, vcc, s4, v34
	s_waitcnt lgkmcnt(0)
	s_nop 0
	v_addc_co_u32_e32 v35, vcc, 0, v35, vcc
	s_barrier
	global_load_dwordx4 v[76:79], v[34:35], off offset:256
	global_load_dwordx4 v[80:83], v[34:35], off offset:288
	global_load_dwordx4 v[84:87], v[34:35], off offset:320
	global_load_dwordx4 v[88:91], v[34:35], off offset:352
	global_load_dwordx4 v[92:95], v[34:35], off offset:384
	global_load_dwordx4 v[96:99], v[34:35], off offset:416
	global_load_dwordx4 v[100:103], v[34:35], off offset:448
	global_load_dwordx4 v[104:107], v[34:35], off offset:480
	v_lshlrev_b32_e32 v0, 8, v36
	v_bitop3_b32 v36, v41, v168, 15 bitop3:0x78
	v_lshl_add_u32 v36, v36, 4, v0
	ds_read_b128 v[44:47], v36 offset:32768
	ds_read_b128 v[48:51], v36 offset:40960
	v_add_u32_e32 v36, 2, v41
	v_bitop3_b32 v36, v36, v168, 15 bitop3:0x78
	v_lshl_add_u32 v36, v36, 4, v0
	ds_read_b128 v[52:55], v36 offset:32768
	ds_read_b128 v[56:59], v36 offset:40960
	v_add_u32_e32 v36, 4, v41
	v_bitop3_b32 v36, v36, v168, 15 bitop3:0x78
	v_lshl_add_u32 v36, v36, 4, v0
	ds_read_b128 v[60:63], v36 offset:32768
	ds_read_b128 v[64:67], v36 offset:40960
	v_add_u32_e32 v36, 6, v41
	v_bitop3_b32 v36, v36, v168, 15 bitop3:0x78
	v_lshl_add_u32 v36, v36, 4, v0
	ds_read_b128 v[68:71], v36 offset:32768
	ds_read_b128 v[72:75], v36 offset:40960
	s_waitcnt vmcnt(7) lgkmcnt(7)
	v_mfma_f32_32x32x16_bf16 v[2:17], v[44:47], v[76:79], v[2:17]
	v_add_u32_e32 v36, 8, v41
	v_bitop3_b32 v36, v36, v168, 15 bitop3:0x78
	v_lshl_add_u32 v36, v36, 4, v0
	ds_read_b128 v[44:47], v36 offset:32768
	s_waitcnt lgkmcnt(7)
	v_mfma_f32_32x32x16_bf16 v[18:33], v[48:51], v[76:79], v[18:33]
	ds_read_b128 v[48:51], v36 offset:40960
	s_waitcnt vmcnt(6) lgkmcnt(7)
	v_mfma_f32_32x32x16_bf16 v[2:17], v[52:55], v[80:83], v[2:17]
	v_add_u32_e32 v36, 10, v41
	v_bitop3_b32 v36, v36, v168, 15 bitop3:0x78
	v_lshl_add_u32 v36, v36, 4, v0
	ds_read_b128 v[52:55], v36 offset:32768
	s_waitcnt lgkmcnt(7)
	v_mfma_f32_32x32x16_bf16 v[18:33], v[56:59], v[80:83], v[18:33]
	ds_read_b128 v[56:59], v36 offset:40960
	s_waitcnt vmcnt(5) lgkmcnt(7)
	v_mfma_f32_32x32x16_bf16 v[2:17], v[60:63], v[84:87], v[2:17]
	v_add_u32_e32 v36, 12, v41
	v_bitop3_b32 v36, v36, v168, 15 bitop3:0x78
	v_lshl_add_u32 v36, v36, 4, v0
	v_add_u32_e32 v41, 14, v41
	v_bitop3_b32 v41, v41, v168, 15 bitop3:0x78
	v_lshl_add_u32 v0, v41, 4, v0
	ds_read_b128 v[60:63], v36 offset:32768
	s_waitcnt lgkmcnt(7)
	v_mfma_f32_32x32x16_bf16 v[18:33], v[64:67], v[84:87], v[18:33]
	ds_read_b128 v[64:67], v36 offset:40960
	s_waitcnt vmcnt(4) lgkmcnt(7)
	v_mfma_f32_32x32x16_bf16 v[2:17], v[68:71], v[88:91], v[2:17]
	ds_read_b128 v[68:71], v0 offset:32768
	s_waitcnt lgkmcnt(7)
	v_mfma_f32_32x32x16_bf16 v[18:33], v[72:75], v[88:91], v[18:33]
	ds_read_b128 v[72:75], v0 offset:40960
	s_waitcnt vmcnt(3) lgkmcnt(7)
	v_mfma_f32_32x32x16_bf16 v[2:17], v[44:47], v[92:95], v[2:17]
	s_waitcnt lgkmcnt(6)
	v_mfma_f32_32x32x16_bf16 v[18:33], v[48:51], v[92:95], v[18:33]
	s_waitcnt vmcnt(2) lgkmcnt(5)
	v_mfma_f32_32x32x16_bf16 v[2:17], v[52:55], v[96:99], v[2:17]
	s_waitcnt lgkmcnt(4)
	v_mfma_f32_32x32x16_bf16 v[18:33], v[56:59], v[96:99], v[18:33]
	s_waitcnt vmcnt(1) lgkmcnt(3)
	v_mfma_f32_32x32x16_bf16 v[2:17], v[60:63], v[100:103], v[2:17]
	s_waitcnt lgkmcnt(2)
	v_mfma_f32_32x32x16_bf16 v[18:33], v[64:67], v[100:103], v[18:33]
	s_waitcnt vmcnt(0) lgkmcnt(1)
	v_mfma_f32_32x32x16_bf16 v[2:17], v[68:71], v[104:107], v[2:17]
	s_waitcnt lgkmcnt(0)
	v_mfma_f32_32x32x16_bf16 v[18:33], v[72:75], v[104:107], v[18:33]

; #define MFMA32(a, b, c) __builtin_amdgcn_mfma_f32_32x32x16_bf16((a), (b), (c), 0, 0, 0)
; DI void state_update(f32x16 (&S)[2], const char* kt, const u16* __restrict__ vt_rows  ,
;                      float cd, int lane) {
;   const int r = lane & 31, h5 = lane >> 5;
; #pragma unroll
;   for (int i = 0; i < 16; ++i) { S[0][i] *= cd; S[1][i] *= cd; }
; #pragma unroll
;   for (int s = 0; s < 8; ++s) {
;     const bf16x8 bv = *(const bf16x8*)(vt_rows + (size_t)r * VT_LD + s * 16 + h5 * 8);
;     const int ch = 2 * s + h5;
;     const bf16x8 a0 = *(const bf16x8*)(kt + r * 256 + ((ch ^ (r & 15)) << 4));
;     const bf16x8 a1 = *(const bf16x8*)(kt + (32 + r) * 256 + ((ch ^ (r & 15)) << 4));
;     S[0] = MFMA32(a0, bv, S[0]);
;     S[1] = MFMA32(a1, bv, S[1]);
;   }
; }
.LBB0_483:
	v_mov_b64_e32 v[34:35], s[46:47]
	v_mad_i64_i32 v[34:35], s[0:1], v174, s12, v[34:35]
	v_lshl_add_u64 v[34:35], s[94:95], 1, v[34:35]
	v_lshl_add_u64 v[34:35], v[0:1], 1, v[34:35]
	v_lshl_add_u64 v[34:35], v[132:133], 1, v[34:35]
	global_load_dwordx4 v[76:79], v[34:35], off
	global_load_dwordx4 v[80:83], v[34:35], off offset:32
	global_load_dwordx4 v[84:87], v[34:35], off offset:64
	global_load_dwordx4 v[88:91], v[34:35], off offset:96
	global_load_dwordx4 v[92:95], v[34:35], off offset:128
	global_load_dwordx4 v[96:99], v[34:35], off offset:160
	global_load_dwordx4 v[100:103], v[34:35], off offset:192
	global_load_dwordx4 v[104:107], v[34:35], off offset:224
	v_lshlrev_b32_e32 v0, 8, v173
	v_xor_b32_e32 v44, v36, v172
	v_lshl_add_u32 v48, v44, 4, v0
	ds_read_b128 v[40:43], v48 offset:32768
	ds_read_b128 v[44:47], v48 offset:40960
	v_pk_mul_f32 v[2:3], v[130:131], v[2:3]
	v_pk_mul_f32 v[18:19], v[130:131], v[18:19]
	v_pk_mul_f32 v[4:5], v[130:131], v[4:5]
	v_pk_mul_f32 v[20:21], v[130:131], v[20:21]
	v_pk_mul_f32 v[6:7], v[130:131], v[6:7]
	v_pk_mul_f32 v[22:23], v[130:131], v[22:23]
	v_pk_mul_f32 v[8:9], v[130:131], v[8:9]
	v_pk_mul_f32 v[24:25], v[130:131], v[24:25]
	v_pk_mul_f32 v[10:11], v[130:131], v[10:11]
	v_pk_mul_f32 v[26:27], v[130:131], v[26:27]
	v_pk_mul_f32 v[12:13], v[130:131], v[12:13]
	v_pk_mul_f32 v[28:29], v[130:131], v[28:29]
	v_pk_mul_f32 v[14:15], v[130:131], v[14:15]
	v_pk_mul_f32 v[30:31], v[130:131], v[30:31]
	v_pk_mul_f32 v[16:17], v[130:131], v[16:17]
	v_pk_mul_f32 v[32:33], v[130:131], v[32:33]
	v_xor_b32_e32 v39, v36, v39
	v_lshl_add_u32 v39, v39, 4, v0
	v_xor_b32_e32 v38, v36, v38
	v_lshl_add_u32 v38, v38, 4, v0
	v_xor_b32_e32 v37, v36, v37
	v_lshl_add_u32 v37, v37, 4, v0
	s_add_i32 s5, s5, 1
	s_cmp_eq_u32 s5, 18
	s_cselect_b64 s[0:1], -1, 0
	ds_read_b128 v[52:55], v39 offset:32768
	ds_read_b128 v[56:59], v39 offset:40960
	ds_read_b128 v[60:63], v38 offset:32768
	ds_read_b128 v[64:67], v38 offset:40960
	ds_read_b128 v[68:71], v37 offset:32768
	ds_read_b128 v[72:75], v37 offset:40960
	s_waitcnt vmcnt(7) lgkmcnt(7)
	v_mfma_f32_32x32x16_bf16 v[2:17], v[40:43], v[76:79], v[2:17]
	v_add_u32_e32 v37, 8, v172
	v_xor_b32_e32 v37, v36, v37
	v_lshl_add_u32 v37, v37, 4, v0
	ds_read_b128 v[40:43], v37 offset:32768
	s_waitcnt lgkmcnt(7)
	v_mfma_f32_32x32x16_bf16 v[18:33], v[44:47], v[76:79], v[18:33]
	ds_read_b128 v[44:47], v37 offset:40960
	s_waitcnt vmcnt(6) lgkmcnt(7)
	v_mfma_f32_32x32x16_bf16 v[2:17], v[52:55], v[80:83], v[2:17]
	v_add_u32_e32 v37, 10, v172
	v_xor_b32_e32 v37, v36, v37
	v_lshl_add_u32 v37, v37, 4, v0
	ds_read_b128 v[52:55], v37 offset:32768
	s_waitcnt lgkmcnt(7)
	v_mfma_f32_32x32x16_bf16 v[18:33], v[56:59], v[80:83], v[18:33]
	ds_read_b128 v[56:59], v37 offset:40960
	s_waitcnt vmcnt(5) lgkmcnt(7)
	v_mfma_f32_32x32x16_bf16 v[2:17], v[60:63], v[84:87], v[2:17]
	v_add_u32_e32 v37, 12, v172
	v_xor_b32_e32 v37, v36, v37
	v_lshl_add_u32 v37, v37, 4, v0
	ds_read_b128 v[60:63], v37 offset:32768
	s_waitcnt lgkmcnt(7)
	v_mfma_f32_32x32x16_bf16 v[18:33], v[64:67], v[84:87], v[18:33]
	ds_read_b128 v[64:67], v37 offset:40960
	s_waitcnt vmcnt(4) lgkmcnt(7)
	v_mfma_f32_32x32x16_bf16 v[2:17], v[68:71], v[88:91], v[2:17]
	v_add_u32_e32 v34, 14, v172
	v_xor_b32_e32 v34, v36, v34
	v_lshl_add_u32 v0, v34, 4, v0
	ds_read_b128 v[68:71], v0 offset:32768
	s_waitcnt lgkmcnt(7)
	v_mfma_f32_32x32x16_bf16 v[18:33], v[72:75], v[88:91], v[18:33]
	ds_read_b128 v[72:75], v0 offset:40960
	s_waitcnt vmcnt(3) lgkmcnt(7)
	v_mfma_f32_32x32x16_bf16 v[2:17], v[40:43], v[92:95], v[2:17]
	s_waitcnt lgkmcnt(6)
	v_mfma_f32_32x32x16_bf16 v[18:33], v[44:47], v[92:95], v[18:33]
	s_waitcnt vmcnt(2) lgkmcnt(5)
	v_mfma_f32_32x32x16_bf16 v[2:17], v[52:55], v[96:99], v[2:17]
	s_waitcnt lgkmcnt(4)
	v_mfma_f32_32x32x16_bf16 v[18:33], v[56:59], v[96:99], v[18:33]
	s_waitcnt vmcnt(1) lgkmcnt(3)
	v_mfma_f32_32x32x16_bf16 v[2:17], v[60:63], v[100:103], v[2:17]
	s_waitcnt lgkmcnt(2)
	v_mfma_f32_32x32x16_bf16 v[18:33], v[64:67], v[100:103], v[18:33]
	s_waitcnt vmcnt(0) lgkmcnt(1)
	v_mfma_f32_32x32x16_bf16 v[2:17], v[68:71], v[104:107], v[2:17]
	s_waitcnt lgkmcnt(0)
	v_mfma_f32_32x32x16_bf16 v[18:33], v[72:75], v[104:107], v[18:33]
	s_and_b64 vcc, exec, s[0:1]
	s_cbranch_vccnz .LBB0_467
